# jump threading of the phase-exit flag chains (one direct branch to the phase-loop tail instead of 3-5 hops through scattered blocks)
# speedup vs baseline: 1.0035x; 1.0035x over previous
.LBB0_114:
	s_mov_b64 s[6:7], 0
	s_mov_b64 s[8:9], 0
	s_and_b64 vcc, exec, s[8:9]
	s_nop 0
	v_and_b32_e32 v188, 63, v186
	s_ashr_i32 s62, s63, 6
	s_andn2_b64 vcc, exec, s[6:7]
	v_readlane_b32 s48, v254, 41
	v_readlane_b32 s49, v254, 42
	s_nop 0
	s_nop 0
	s_and_b64 vcc, exec, s[12:13]
	s_branch .Ltramp_0
	s_mov_b64 s[6:7], 0

.LBB0_158:
	s_mov_b64 s[6:7], 0
	s_nop 0
	s_andn2_b64 vcc, exec, s[6:7]
	v_readlane_b32 s48, v254, 41
	v_readlane_b32 s49, v254, 42
	s_nop 0
	s_and_b64 vcc, exec, s[10:11]
	s_branch .Ltramp_1
	s_mov_b64 s[6:7], 0

.LBB0_206:
	s_mov_b64 s[6:7], 0
	s_andn2_b64 vcc, exec, s[6:7]
	v_readlane_b32 s48, v254, 41
	v_readlane_b32 s49, v254, 42
	s_nop 0
	s_mov_b64 s[6:7], 0
	s_andn2_b64 vcc, exec, s[6:7]
	s_nop 0
	s_mov_b64 s[6:7], 0
	s_andn2_b64 vcc, exec, s[6:7]
	s_nop 0
	s_mov_b64 s[10:11], 0
	s_and_b64 vcc, exec, s[10:11]
	s_nop 0
	s_mov_b64 s[12:13], 0
	s_and_b64 vcc, exec, s[12:13]
	s_nop 0
	s_branch .Ltramp_2
	s_mov_b64 s[6:7], 0

.LBB0_272:
	s_mov_b64 s[6:7], 0
	v_readlane_b32 s56, v254, 35
	s_and_b64 vcc, exec, s[6:7]
	v_readlane_b32 s57, v254, 36
	s_nop 0
	s_mov_b64 s[6:7], 0
	s_andn2_b64 vcc, exec, s[6:7]
	s_nop 0
	s_mov_b64 s[6:7], 0
	s_andn2_b64 vcc, exec, s[6:7]
	s_nop 0
	s_mov_b64 s[10:11], 0
	s_and_b64 vcc, exec, s[10:11]
	s_nop 0
	s_mov_b64 s[12:13], 0
	s_and_b64 vcc, exec, s[12:13]
	s_nop 0
	s_branch .Ltramp_2
	s_mov_b64 s[6:7], 0

.LBB0_319:
	s_mov_b64 s[6:7], 0
	s_andn2_b64 vcc, exec, s[6:7]
	s_nop 0
	s_mov_b64 s[6:7], 0
	s_andn2_b64 vcc, exec, s[6:7]
	s_nop 0
	s_mov_b64 s[10:11], 0
	s_and_b64 vcc, exec, s[10:11]
	s_nop 0
	s_mov_b64 s[12:13], 0
	s_and_b64 vcc, exec, s[12:13]
	s_nop 0
	s_branch .Lthr_2
	s_mov_b64 s[6:7], 0

.LBB0_359:
	s_mov_b64 s[6:7], 0
	s_andn2_b64 vcc, exec, s[6:7]
	s_nop 0
	s_mov_b64 s[10:11], 0
	s_and_b64 vcc, exec, s[10:11]
	s_nop 0
	s_mov_b64 s[12:13], 0
	s_and_b64 vcc, exec, s[12:13]
	s_nop 0
	s_branch .Lthr_2

.Ltramp_2:
	s_branch .Lthr_2
	s_mov_b64 s[6:7], 0

.LBB0_432:
	s_mov_b64 s[6:7], 0
	s_nop 0
	s_andn2_b64 vcc, exec, s[6:7]
	v_readlane_b32 s48, v254, 41
	v_readlane_b32 s49, v254, 42
	s_nop 0
	s_mov_b64 s[10:11], 0
	s_and_b64 vcc, exec, s[10:11]
	s_nop 0
	s_mov_b64 s[12:13], 0
	s_and_b64 vcc, exec, s[12:13]
	s_nop 0
	s_branch .Lthr_2
	s_mov_b64 s[6:7], 0

.LBB0_574:
	s_mov_b64 s[10:11], 0
	s_and_b64 vcc, exec, s[10:11]
	s_nop 0
	s_mov_b64 s[12:13], 0
	s_and_b64 vcc, exec, s[12:13]
	s_nop 0
	s_branch .Lthr_2
	s_mov_b64 s[10:11], 0

.Lthr_1:
	s_cbranch_vccz .LBB0_693
	s_cmp_eq_u32 s92, 2
	s_cselect_b64 s[10:11], -1, 0
	s_and_b64 s[6:7], s[10:11], exec
	s_mov_b32 s6, 0xe00000
	s_cselect_b32 s6, s6, 0x2b80000
	s_add_u32 s25, s20, s6
	s_addc_u32 s52, s21, 0
	s_mov_b64 s[8:9], -1
	s_mov_b64 s[12:13], 0
	s_cmp_lt_i32 s22, 25
	s_mov_b64 s[6:7], 0
	s_cbranch_scc1 .LBB0_604
	s_cmp_eq_u32 s22, 25
	s_mov_b64 s[6:7], -1
	s_cbranch_scc0 .LBB0_603
	v_readlane_b32 s6, v251, 45
	s_waitcnt vmcnt(0)
	v_mov_b32_e32 v16, v217
	v_readlane_b32 s7, v251, 46
	s_andn2_b64 vcc, exec, s[6:7]
	v_readfirstlane_b32 s6, v16
	s_cbranch_vccnz .LBB0_602
	v_lshlrev_b32_e32 v1, 4, v16
	v_add_u32_e32 v0, 0x2000, v1
	v_ashrrev_i32_e32 v3, 31, v0
	v_lshrrev_b32_e32 v3, 22, v3
	v_add_u32_e32 v3, v0, v3
	v_ashrrev_i32_e32 v8, 10, v3
	v_mul_i32_i24_e32 v3, 0x400, v8
	v_sub_u32_e32 v0, v0, v3
	v_lshrrev_b32_e32 v3, 4, v0
	v_bitop3_b32 v0, v3, v0, 32 bitop3:0x6c
	v_ashrrev_i32_e32 v3, 31, v0
	v_lshrrev_b32_e32 v3, 26, v3
	v_add_u32_e32 v3, v0, v3
	v_lshlrev_b32_e32 v4, 3, v8
	v_ashrrev_i32_e32 v9, 6, v3
	v_and_b32_e32 v4, -16, v4
	v_add_u32_e32 v4, v9, v4
	s_waitcnt lgkmcnt(0)
	v_and_b32_e32 v5, 3, v9
	s_mov_b32 s14, 0xffffe0
	v_lshrrev_b32_e32 v6, 2, v4
	v_lshlrev_b32_e32 v7, 1, v4
	v_and_b32_e32 v3, 0xc0, v3
	v_and_or_b32 v5, v4, s14, v5
	v_and_b32_e32 v6, 4, v6
	v_and_b32_e32 v7, 24, v7
	v_sub_u32_e32 v0, v0, v3
	v_mov_b32_e32 v15, 1
	v_or3_b32 v5, v5, v6, v7
	v_lshlrev_b32_e32 v6, 5, v8
	v_ashrrev_i16_sdwa v0, v15, sext(v0) dst_sel:DWORD dst_unused:UNUSED_PAD src0_sel:DWORD src1_sel:BYTE_0
	v_and_b32_e32 v10, 32, v6
	v_bfe_i32 v11, v0, 0, 16
	s_movk_i32 s9, 0xb00
	v_mul_u32_u24_e32 v5, 0xb00, v5
	v_add_u32_e32 v3, v10, v11
	v_mul_lo_u32 v4, v4, s9
	v_add_lshl_u32 v0, v5, v3, 1
	v_add_lshl_u32 v152, v3, v4, 1
	v_bfe_i32 v3, v16, 27, 1
	v_lshrrev_b32_e32 v3, 22, v3
	v_add_u32_e32 v3, v1, v3
	v_and_b32_e32 v3, 0xfffffc00, v3
	v_sub_u32_e32 v1, v1, v3
	v_lshrrev_b32_e32 v3, 4, v1
	v_ashrrev_i32_e32 v4, 31, v16
	v_bitop3_b32 v1, v3, v1, 32 bitop3:0x6c
	v_lshrrev_b32_e32 v4, 26, v4
	v_ashrrev_i32_e32 v3, 31, v1
	v_add_u32_e32 v4, v16, v4
	v_lshrrev_b32_e32 v3, 26, v3
	v_ashrrev_i32_e32 v13, 6, v4
	v_add_u32_e32 v3, v1, v3
	v_lshlrev_b32_e32 v4, 3, v13
	v_ashrrev_i32_e32 v12, 6, v3
	v_and_b32_e32 v4, -16, v4
	v_add_u32_e32 v4, v12, v4
	v_and_b32_e32 v5, 3, v12
	v_lshrrev_b32_e32 v6, 2, v4
	v_lshlrev_b32_e32 v7, 1, v4
	v_and_b32_e32 v3, 0xc0, v3
	s_ashr_i32 s7, s6, 6
	v_and_or_b32 v5, v4, s14, v5
	v_and_b32_e32 v6, 4, v6
	v_and_b32_e32 v7, 24, v7
	v_sub_u32_e32 v1, v1, v3
	s_ashr_i32 s8, s6, 8
	s_lshl_b32 s48, s7, 10
	v_or3_b32 v5, v5, v6, v7
	v_lshlrev_b32_e32 v6, 5, v13
	v_ashrrev_i16_sdwa v1, v15, sext(v1) dst_sel:DWORD dst_unused:UNUSED_PAD src0_sel:DWORD src1_sel:BYTE_0
	v_mul_lo_u32 v3, v4, s9
	v_readlane_b32 s9, v254, 13
	v_and_b32_e32 v14, 32, v6
	v_bfe_i32 v15, v1, 0, 16
	s_add_u32 s36, s25, s9
	v_readlane_b32 s9, v254, 11
	v_mul_u32_u24_e32 v5, 0xb00, v5
	v_add_u32_e32 v1, v14, v15
	s_addc_u32 s37, s52, s9
	s_add_i32 s49, s48, 0
	v_add_lshl_u32 v180, v5, v1, 1
	s_add_i32 m0, s49, 0x10000
	v_add_lshl_u32 v154, v1, v3, 1
	global_load_lds_dwordx4 v180, s[36:37]
	s_add_i32 m0, s49, 0x12000
	s_add_u32 s14, s36, 0xb0000
	global_load_lds_dwordx4 v0, s[36:37]
	s_addc_u32 s15, s37, 0
	s_add_i32 m0, s49, 0x14000
	s_add_i32 s50, s49, 0x2000
	global_load_lds_dwordx4 v180, s[14:15]
	s_add_i32 m0, s49, 0x16000
	s_add_i32 s51, s49, 0x4000
	global_load_lds_dwordx4 v0, s[14:15]
	v_readlane_b32 s14, v253, 14
	s_mov_b32 m0, s49
	v_readlane_b32 s15, v253, 15
	s_add_i32 s53, s49, 0x6000
	v_mov_b32_e32 v1, v181
	s_cmp_eq_u32 s8, 1
	v_lshl_add_u64 v[4:5], s[36:37], 0, v[180:181]
	v_lshl_add_u64 v[6:7], s[36:37], 0, v[0:1]
	global_load_lds_dwordx4 v154, s[14:15]
	s_mov_b32 m0, s50
	s_nop 0
	global_load_lds_dwordx4 v152, s[14:15]
	v_readlane_b32 s14, v253, 16
	s_mov_b32 m0, s51
	v_readlane_b32 s15, v253, 17
	s_nop 4
	global_load_lds_dwordx4 v154, s[14:15]
	s_mov_b32 m0, s53
	s_nop 0
	global_load_lds_dwordx4 v152, s[14:15]
	s_cselect_b64 s[14:15], -1, 0
	s_cmp_lg_u32 s8, 1
	s_cbranch_scc1 .LBB0_581
	s_barrier

.LBB0_649:
	s_mov_b64 s[12:13], 0
	s_andn2_b64 vcc, exec, s[12:13]
	v_readlane_b32 s48, v254, 41
	v_readlane_b32 s49, v254, 42
	s_nop 0
	s_mov_b64 s[12:13], 0
	s_and_b64 vcc, exec, s[12:13]
	s_nop 0
	s_branch .Lthr_2
	s_mov_b64 s[12:13], 0

.Lthr_0:
	s_cbranch_vccz .LBB0_871
	v_readlane_b32 s6, v250, 27
	s_add_i32 s25, s62, s6
	s_add_i32 s6, s22, 12
	s_cmp_lt_u32 s6, 25
	s_cselect_b64 s[8:9], -1, 0
	s_and_b64 s[6:7], s[8:9], exec
	s_movk_i32 s6, 0x3600
	s_cselect_b32 s44, s6, 0x2e00
	s_cmp_ge_i32 s25, s44
	s_cbranch_scc1 .LBB0_850
	v_and_b32_e32 v1, 7, v186
	v_readlane_b32 s12, v250, 32
	v_lshlrev_b32_e32 v180, 4, v1
	v_readlane_b32 s13, v250, 33
	v_readlane_b32 s10, v250, 28
	v_readlane_b32 s11, v250, 29
	v_lshl_add_u64 v[44:45], s[12:13], 0, v[180:181]
	v_readlane_b32 s12, v250, 34
	v_readlane_b32 s13, v250, 35
	v_lshrrev_b32_e32 v0, 3, v188
	s_movk_i32 s1, 0x84
	v_lshl_add_u64 v[46:47], s[12:13], 0, v[180:181]
	v_readlane_b32 s12, v250, 36
	v_readlane_b32 s13, v250, 37
	s_waitcnt lgkmcnt(0)
	v_mov_b32_e32 v5, 0x840
	v_lshl_add_u64 v[40:41], s[10:11], 0, v[180:181]
	v_lshl_add_u64 v[48:49], s[12:13], 0, v[180:181]
	v_readlane_b32 s12, v250, 38
	v_readlane_b32 s13, v250, 39
	v_readlane_b32 s10, v250, 30
	s_lshl_b32 s6, s62, 14
	v_lshl_add_u64 v[50:51], s[12:13], 0, v[180:181]
	v_readlane_b32 s12, v250, 40
	v_readlane_b32 s13, v250, 41
	v_mad_u32_u24 v87, v0, s1, v5
	v_mov_b32_e32 v5, 0xc60
	v_lshl_add_u64 v[52:53], s[12:13], 0, v[180:181]
	v_readlane_b32 s12, v250, 42
	v_readlane_b32 s11, v250, 31
	v_readlane_b32 s13, v250, 43
	s_add_i32 s6, s6, 0
	v_lshlrev_b32_e32 v4, 2, v1
	v_mad_u32_u24 v89, v0, s1, v5
	v_mul_u32_u24_e32 v1, 0x420, v1
	v_lshlrev_b32_e32 v5, 2, v0
	s_ashr_i32 s1, s0, 31
	v_lshl_add_u64 v[42:43], s[10:11], 0, v[180:181]
	s_lshl_b32 s10, s0, 10
	v_lshl_add_u64 v[54:55], s[12:13], 0, v[180:181]
	v_readlane_b32 s12, v250, 44
	s_mov_b64 s[26:27], s[60:61]
	v_readlane_b32 s48, v251, 4
	v_add_u32_e32 v3, s6, v180
	v_add3_u32 v90, s6, v1, v5
	s_lshl_b64 s[6:7], s[0:1], 22
	s_ashr_i32 s11, s10, 31
	v_readlane_b32 s13, v250, 45
	v_readlane_b32 s52, v251, 8
	v_readlane_b32 s53, v251, 9
	v_lshl_add_u64 v[56:57], s[12:13], 0, v[180:181]
	s_add_u32 s12, s52, s6
	v_readlane_b32 s68, v250, 48
	s_addc_u32 s13, s53, s7
	v_readlane_b32 s82, v250, 62
	v_lshl_add_u64 v[58:59], s[12:13], 0, v[180:181]
	v_readlane_b32 s83, v250, 63
	s_add_u32 s12, s82, s6
	v_readlane_b32 s78, v250, 58
	s_addc_u32 s13, s83, s7
	s_lshl_b64 s[16:17], s[10:11], 2
	v_readlane_b32 s79, v250, 59
	s_add_u32 s10, s78, s16
	v_readlane_b32 s76, v250, 56
	s_addc_u32 s11, s79, s17
	v_readlane_b32 s69, v250, 49
	v_readlane_b32 s70, v250, 50
	v_readlane_b32 s71, v250, 51
	v_readlane_b32 s72, v250, 52
	v_readlane_b32 s73, v250, 53
	v_readlane_b32 s74, v250, 54
	v_readlane_b32 s75, v250, 55
	v_readlane_b32 s77, v250, 57
	v_readlane_b32 s80, v250, 60
	v_readlane_b32 s81, v250, 61
	s_add_u32 s6, s76, s6
	s_addc_u32 s7, s77, s7
	v_readlane_b32 s68, v251, 22
	s_mul_i32 s15, s0, 0xe08000
	v_readlane_b32 s82, v251, 36
	s_mul_hi_i32 s14, s0, 0xe08000
	v_lshl_add_u64 v[62:63], s[6:7], 0, v[180:181]
	v_readlane_b32 s83, v251, 37
	s_add_u32 s6, s82, s15
	v_readlane_b32 s80, v251, 34
	s_addc_u32 s7, s83, s14
	v_lshl_add_u64 v[60:61], s[12:13], 0, v[180:181]
	v_readlane_b32 s81, v251, 35
	s_add_u32 s12, s80, s16
	s_mul_i32 s19, s0, 0xb00000
	v_readlane_b32 s60, v251, 16
	s_addc_u32 s13, s81, s17
	s_mul_hi_i32 s18, s0, 0xb00000
	v_readlane_b32 s61, v251, 17
	v_lshl_add_u64 v[64:65], s[6:7], 0, v[180:181]
	s_add_u32 s6, s60, s19
	v_readlane_b32 s58, v251, 14
	s_addc_u32 s7, s61, s18
	v_readlane_b32 s59, v251, 15
	v_lshl_add_u64 v[66:67], s[6:7], 0, v[180:181]
	s_add_u32 s6, s58, s19
	v_readlane_b32 s54, v251, 10
	s_addc_u32 s7, s59, s18
	v_readlane_b32 s55, v251, 11
	s_add_u32 s14, s54, s16
	v_readlane_b32 s56, v251, 12
	s_addc_u32 s15, s55, s17
	v_readlane_b32 s57, v251, 13
	v_lshl_add_u64 v[68:69], s[6:7], 0, v[180:181]
	s_add_u32 s6, s56, s19
	v_readlane_b32 s78, v251, 32
	s_addc_u32 s7, s57, s18
	v_readlane_b32 s79, v251, 33
	v_lshl_add_u64 v[70:71], s[6:7], 0, v[180:181]
	s_add_u32 s6, s78, s19
	v_readlane_b32 s76, v251, 30
	s_addc_u32 s7, s79, s18
	v_readlane_b32 s77, v251, 31
	v_lshl_add_u64 v[72:73], s[6:7], 0, v[180:181]
	s_add_u32 s6, s76, s19
	v_readlane_b32 s72, v251, 26
	s_addc_u32 s7, s77, s18
	v_readlane_b32 s73, v251, 27
	s_add_u32 s16, s72, s16
	v_readlane_b32 s74, v251, 28
	s_addc_u32 s17, s73, s17
	v_readlane_b32 s75, v251, 29
	v_lshl_add_u64 v[74:75], s[6:7], 0, v[180:181]
	s_add_u32 s6, s74, s19
	s_addc_u32 s7, s75, s18
	v_readlane_b32 s49, v251, 5
	v_readlane_b32 s50, v251, 6
	v_readlane_b32 s51, v251, 7
	v_readlane_b32 s56, v254, 35
	v_lshl_add_u64 v[76:77], s[6:7], 0, v[180:181]
	s_lshl_b32 s6, s25, 1
	v_mul_u32_u24_e32 v84, 0x84, v0
	v_or_b32_e32 v85, 8, v0
	v_or_b32_e32 v86, 16, v0
	v_or_b32_e32 v88, 24, v0
	s_movk_i32 s1, 0xb1
	s_mov_b64 s[60:61], s[26:27]
	v_readlane_b32 s57, v254, 36
	v_mov_b32_e32 v1, v181
	s_lshl_b32 s45, s25, 5
	s_lshl_b32 s46, s96, 5
	s_lshl_b32 s47, s25, 6
	s_lshl_b32 s48, s96, 6
	s_add_i32 s49, s6, 0xffffa400
	s_lshl_b32 s50, s96, 1
	v_lshlrev_b32_e32 v78, 2, v4
	s_mov_b32 s51, s25
	v_readlane_b32 s62, v251, 18
	v_readlane_b32 s63, v251, 19
	v_readlane_b32 s69, v251, 23
	v_readlane_b32 s70, v251, 24
	v_readlane_b32 s71, v251, 25
	s_branch .LBB0_699

.LBB0_698:
.Lthr_3:
	s_add_i32 s51, s51, s96
	s_add_i32 s45, s45, s46
	s_add_i32 s47, s47, s48
	s_add_i32 s49, s49, s50
	s_cmp_ge_i32 s51, s44
	s_cbranch_scc1 .LBB0_850

.LBB0_724:
	s_mov_b64 s[6:7], 0
	s_andn2_b64 vcc, exec, s[6:7]
	s_nop 0
	s_mov_b64 s[6:7], 0
	s_andn2_b64 vcc, exec, s[6:7]
	s_nop 0
	s_mov_b64 s[6:7], 0
	s_andn2_b64 vcc, exec, s[6:7]
	s_nop 0
	s_mov_b64 s[6:7], 0
	s_andn2_b64 vcc, exec, s[6:7]
	s_nop 0
	s_mov_b64 s[6:7], 0
	s_andn2_b64 vcc, exec, s[6:7]
	s_nop 0
	s_mov_b64 s[6:7], 0
	s_andn2_b64 vcc, exec, s[6:7]
	s_nop 0
	s_mov_b64 s[6:7], 0
	s_andn2_b64 vcc, exec, s[6:7]
	s_nop 0
	s_mov_b64 s[6:7], 0
	s_andn2_b64 vcc, exec, s[6:7]
	s_nop 0
	s_mov_b64 s[6:7], 0
	s_andn2_b64 vcc, exec, s[6:7]
	s_nop 0
	s_branch .Lthr_3
	s_mov_b64 s[6:7], 0

.LBB0_739:
	s_mov_b64 s[6:7], 0
	s_andn2_b64 vcc, exec, s[6:7]
	s_nop 0
	s_mov_b64 s[6:7], 0
	s_andn2_b64 vcc, exec, s[6:7]
	s_nop 0
	s_mov_b64 s[6:7], 0
	s_andn2_b64 vcc, exec, s[6:7]
	s_nop 0
	s_mov_b64 s[6:7], 0
	s_andn2_b64 vcc, exec, s[6:7]
	s_nop 0
	s_mov_b64 s[6:7], 0
	s_andn2_b64 vcc, exec, s[6:7]
	s_nop 0
	s_mov_b64 s[6:7], 0
	s_andn2_b64 vcc, exec, s[6:7]
	s_nop 0
	s_mov_b64 s[6:7], 0
	s_andn2_b64 vcc, exec, s[6:7]
	s_nop 0
	s_mov_b64 s[6:7], 0
	s_andn2_b64 vcc, exec, s[6:7]
	s_nop 0
	s_branch .Lthr_3
	s_mov_b64 s[6:7], 0

.LBB0_742:
	s_mov_b64 s[6:7], 0
	s_andn2_b64 vcc, exec, s[6:7]
	s_nop 0
	s_mov_b64 s[6:7], 0
	s_andn2_b64 vcc, exec, s[6:7]
	s_nop 0
	s_mov_b64 s[6:7], 0
	s_andn2_b64 vcc, exec, s[6:7]
	s_nop 0
	s_mov_b64 s[6:7], 0
	s_andn2_b64 vcc, exec, s[6:7]
	s_nop 0
	s_mov_b64 s[6:7], 0
	s_andn2_b64 vcc, exec, s[6:7]
	s_nop 0
	s_mov_b64 s[6:7], 0
	s_andn2_b64 vcc, exec, s[6:7]
	s_nop 0
	s_mov_b64 s[6:7], 0
	s_andn2_b64 vcc, exec, s[6:7]
	s_nop 0
	s_branch .Lthr_3
	s_mov_b64 s[6:7], 0

.LBB0_757:
	s_mov_b64 s[6:7], 0
	s_andn2_b64 vcc, exec, s[6:7]
	s_nop 0
	s_mov_b64 s[6:7], 0
	s_andn2_b64 vcc, exec, s[6:7]
	s_nop 0
	s_mov_b64 s[6:7], 0
	s_andn2_b64 vcc, exec, s[6:7]
	s_nop 0
	s_mov_b64 s[6:7], 0
	s_andn2_b64 vcc, exec, s[6:7]
	s_nop 0
	s_mov_b64 s[6:7], 0
	s_andn2_b64 vcc, exec, s[6:7]
	s_nop 0
	s_mov_b64 s[6:7], 0
	s_andn2_b64 vcc, exec, s[6:7]
	s_nop 0
	s_branch .Lthr_3
	s_mov_b64 s[6:7], 0

.LBB0_760:
	s_mov_b64 s[6:7], 0
	s_andn2_b64 vcc, exec, s[6:7]
	s_nop 0
	s_mov_b64 s[6:7], 0
	s_andn2_b64 vcc, exec, s[6:7]
	s_nop 0
	s_mov_b64 s[6:7], 0
	s_andn2_b64 vcc, exec, s[6:7]
	s_nop 0
	s_mov_b64 s[6:7], 0
	s_andn2_b64 vcc, exec, s[6:7]
	s_nop 0
	s_mov_b64 s[6:7], 0
	s_andn2_b64 vcc, exec, s[6:7]
	s_nop 0
	s_branch .Lthr_3
	s_mov_b64 s[6:7], 0

.LBB0_775:
	s_mov_b64 s[6:7], 0
	s_andn2_b64 vcc, exec, s[6:7]
	s_nop 0
	s_mov_b64 s[6:7], 0
	s_andn2_b64 vcc, exec, s[6:7]
	s_nop 0
	s_mov_b64 s[6:7], 0
	s_andn2_b64 vcc, exec, s[6:7]
	s_nop 0
	s_mov_b64 s[6:7], 0
	s_andn2_b64 vcc, exec, s[6:7]
	s_nop 0
	s_branch .Lthr_3
	s_mov_b64 s[6:7], 0

.LBB0_790:
	s_mov_b64 s[6:7], 0
	s_andn2_b64 vcc, exec, s[6:7]
	s_nop 0
	s_mov_b64 s[6:7], 0
	s_andn2_b64 vcc, exec, s[6:7]
	s_nop 0
	s_mov_b64 s[6:7], 0
	s_andn2_b64 vcc, exec, s[6:7]
	s_nop 0
	s_branch .Lthr_3
	s_mov_b64 s[6:7], 0

.LBB0_793:
	s_mov_b64 s[6:7], 0
	s_andn2_b64 vcc, exec, s[6:7]
	s_nop 0
	s_mov_b64 s[6:7], 0
	s_andn2_b64 vcc, exec, s[6:7]
	s_nop 0
	s_branch .Lthr_3
	s_mov_b64 s[6:7], 0

.LBB0_871:
.Lthr_2:
	s_add_i32 s22, s22, 1
	s_cmp_ge_i32 s22, s23
	s_cselect_b64 s[6:7], -1, 0
	s_cmp_eq_u32 s92, 9
	s_cselect_b64 s[8:9], -1, 0
	s_or_b64 s[8:9], s[6:7], s[8:9]
	s_and_b64 vcc, exec, s[8:9]
	s_cbranch_vccz .LBB0_872
	s_getpc_b64 s[98:99]
